# attention softmax/PV block: V^T fragment reads hoisted to block top, exps in groups of 8 with each PV MFMA pair issued as soon as its probabilities are packed (MFMA/LDS under exp work); bit-identical
# baseline (speedup 1.0000x reference)
; #define LAS __attribute__((address_space(3)))
; __device__ __forceinline__ unsigned pk2(float lo, float hi) { f32x2 v = {lo, hi}; bf16x2_t b = __builtin_convertvector(v, bf16x2_t); return __builtin_bit_cast(unsigned, b); }
; template <bool MLA>
; __device__ __forceinline__ void attn_unit(LAS unsigned char* lds, const bf16_t* Q, const bf16_t* Kp, const bf16_t* V, bf16_t* O, const float* ssq_qn, const float* ssq_qr, const float* cl, int b, int h, int qb) {
;     ...
;             float ls = 0.f;
; #pragma unroll
;             for (int i = 0; i < 16; ++i) { p0[i] = __builtin_amdgcn_exp2f(p0[i] - m_new); p1[i] = __builtin_amdgcn_exp2f(p1[i] - m_new); ls += p0[i] + p1[i]; }
;             if (__any(m_new > m_run)) {
;                 const float alpha = __builtin_amdgcn_exp2f(m_run - m_new);
;                 l_run *= alpha;
; #pragma unroll
;                 for (int i = 0; i < 16; ++i) { o0[i] *= alpha; o1[i] *= alpha; }
;             }
;             l_run += ls; m_run = m_new;
;             bf16x8 pb[4];
; #pragma unroll
;             for (int s = 0; s < 4; ++s) { u32x4 wv;
; #pragma unroll
;                 for (int jj = 0; jj < 4; ++jj) wv[jj] = (s < 2) ? pk2(p0[8 * (s & 1) + 2 * jj], p0[8 * (s & 1) + 2 * jj + 1]) : pk2(p1[8 * (s & 1) + 2 * jj], p1[8 * (s & 1) + 2 * jj + 1]);
;                 pb[s] = __builtin_bit_cast(bf16x8, wv); }
;             const LAS unsigned char* vb = lds + VOFF + buf * VBUF + (4 * hh + ((r & 15) >> 2)) * VP + (16 * (r >> 4) + 4 * (r & 3)) * 2;
; #pragma unroll
;             for (int s = 0; s < 4; ++s) {
;                 const v4i16_t lo0 = __builtin_amdgcn_ds_read_tr16_b64_v4i16((LAS v4i16_t*)(vb + s * 16 * VP)), hi0 = __builtin_amdgcn_ds_read_tr16_b64_v4i16((LAS v4i16_t*)(vb + s * 16 * VP + 8 * VP));
;                 const v4i16_t lo1 = __builtin_amdgcn_ds_read_tr16_b64_v4i16((LAS v4i16_t*)(vb + s * 16 * VP + 64)), hi1 = __builtin_amdgcn_ds_read_tr16_b64_v4i16((LAS v4i16_t*)(vb + s * 16 * VP + 8 * VP + 64));
;                 const bf16x8 a0 = (bf16x8){lo0[0], lo0[1], lo0[2], lo0[3], hi0[0], hi0[1], hi0[2], hi0[3]}, a1 = (bf16x8){lo1[0], lo1[1], lo1[2], lo1[3], hi1[0], hi1[1], hi1[2], hi1[3]};
;                 o0 = __builtin_amdgcn_mfma_f32_32x32x16_bf16(a0, pb[s], o0, 0, 0, 0);
;                 o1 = __builtin_amdgcn_mfma_f32_32x32x16_bf16(a1, pb[s], o1, 0, 0, 0);
;             }
.LBB0_362:
	s_mul_i32 s8, s40, 0x3000
	v_add_u32_e32 v130, s8, v120
	ds_read_b64_tr_b16 v[200:201], v130 offset:26624
	ds_read_b64_tr_b16 v[202:203], v130 offset:28160
	ds_read_b64_tr_b16 v[204:205], v130 offset:26688
	ds_read_b64_tr_b16 v[206:207], v130 offset:28224
	ds_read_b64_tr_b16 v[208:209], v130 offset:29696
	ds_read_b64_tr_b16 v[210:211], v130 offset:31232
	ds_read_b64_tr_b16 v[212:213], v130 offset:29760
	ds_read_b64_tr_b16 v[214:215], v130 offset:31296
	ds_read_b64_tr_b16 v[216:217], v130 offset:32768
	ds_read_b64_tr_b16 v[218:219], v130 offset:34304
	ds_read_b64_tr_b16 v[220:221], v130 offset:32832
	ds_read_b64_tr_b16 v[222:223], v130 offset:34368
	v_sub_f32_e32 v50, v50, v0
	v_sub_f32_e32 v51, v51, v0
	v_exp_f32_e32 v50, v50
	v_exp_f32_e32 v51, v51
	v_sub_f32_e32 v52, v52, v0
	v_sub_f32_e32 v53, v53, v0
	v_exp_f32_e32 v52, v52
	v_exp_f32_e32 v53, v53
	v_sub_f32_e32 v54, v54, v0
	v_sub_f32_e32 v55, v55, v0
	v_exp_f32_e32 v54, v54
	v_exp_f32_e32 v55, v55
	v_sub_f32_e32 v56, v56, v0
	v_sub_f32_e32 v57, v57, v0
	v_exp_f32_e32 v56, v56
	v_exp_f32_e32 v57, v57
	v_cvt_pk_bf16_f32 v180, v50, v51
	v_cvt_pk_bf16_f32 v181, v52, v53
	v_cvt_pk_bf16_f32 v182, v54, v55
	v_cvt_pk_bf16_f32 v183, v56, v57
	s_waitcnt lgkmcnt(8)
	ds_read_b64_tr_b16 v[224:225], v130 offset:35840
	ds_read_b64_tr_b16 v[226:227], v130 offset:37376
	ds_read_b64_tr_b16 v[228:229], v130 offset:35904
	ds_read_b64_tr_b16 v[230:231], v130 offset:37440
	v_mfma_f32_32x32x16_bf16 v[18:33], v[200:203], v[180:183], v[18:33]
	v_mfma_f32_32x32x16_bf16 v[2:17], v[204:207], v[180:183], v[2:17]
	v_sub_f32_e32 v58, v58, v0
	v_sub_f32_e32 v59, v59, v0
	v_exp_f32_e32 v58, v58
	v_exp_f32_e32 v59, v59
	v_sub_f32_e32 v60, v60, v0
	v_sub_f32_e32 v61, v61, v0
	v_exp_f32_e32 v60, v60
	v_exp_f32_e32 v61, v61
	v_sub_f32_e32 v62, v62, v0
	v_sub_f32_e32 v63, v63, v0
	v_exp_f32_e32 v62, v62
	v_exp_f32_e32 v63, v63
	v_sub_f32_e32 v64, v64, v0
	v_sub_f32_e32 v65, v65, v0
	v_exp_f32_e32 v64, v64
	v_exp_f32_e32 v65, v65
	v_cvt_pk_bf16_f32 v184, v58, v59
	v_cvt_pk_bf16_f32 v185, v60, v61
	v_cvt_pk_bf16_f32 v186, v62, v63
	v_cvt_pk_bf16_f32 v187, v64, v65
	s_waitcnt lgkmcnt(8)
	s_nop 0
	v_mfma_f32_32x32x16_bf16 v[18:33], v[208:211], v[184:187], v[18:33]
	v_mfma_f32_32x32x16_bf16 v[2:17], v[212:215], v[184:187], v[2:17]
	v_sub_f32_e32 v34, v34, v0
	v_sub_f32_e32 v35, v35, v0
	v_exp_f32_e32 v34, v34
	v_exp_f32_e32 v35, v35
	v_add_f32_e32 v179, v34, v50
	v_add_f32_e32 v178, 0, v179
	v_add_f32_e32 v179, v35, v51
	v_add_f32_e32 v178, v179, v178
	v_sub_f32_e32 v36, v36, v0
	v_sub_f32_e32 v37, v37, v0
	v_exp_f32_e32 v36, v36
	v_exp_f32_e32 v37, v37
	v_add_f32_e32 v179, v36, v52
	v_add_f32_e32 v178, v179, v178
	v_add_f32_e32 v179, v37, v53
	v_add_f32_e32 v178, v179, v178
	v_sub_f32_e32 v38, v38, v0
	v_sub_f32_e32 v39, v39, v0
	v_exp_f32_e32 v38, v38
	v_exp_f32_e32 v39, v39
	v_add_f32_e32 v179, v38, v54
	v_add_f32_e32 v178, v179, v178
	v_add_f32_e32 v179, v39, v55
	v_add_f32_e32 v178, v179, v178
	v_sub_f32_e32 v40, v40, v0
	v_sub_f32_e32 v41, v41, v0
	v_exp_f32_e32 v40, v40
	v_exp_f32_e32 v41, v41
	v_add_f32_e32 v179, v40, v56
	v_add_f32_e32 v178, v179, v178
	v_add_f32_e32 v179, v41, v57
	v_add_f32_e32 v178, v179, v178
	v_cvt_pk_bf16_f32 v188, v34, v35
	v_cvt_pk_bf16_f32 v189, v36, v37
	v_cvt_pk_bf16_f32 v190, v38, v39
	v_cvt_pk_bf16_f32 v191, v40, v41
	s_waitcnt lgkmcnt(4)
	s_nop 0
	v_mfma_f32_32x32x16_bf16 v[18:33], v[216:219], v[188:191], v[18:33]
	v_mfma_f32_32x32x16_bf16 v[2:17], v[220:223], v[188:191], v[2:17]
	v_sub_f32_e32 v42, v42, v0
	v_sub_f32_e32 v43, v43, v0
	v_exp_f32_e32 v42, v42
	v_exp_f32_e32 v43, v43
	v_add_f32_e32 v179, v42, v58
	v_add_f32_e32 v178, v179, v178
	v_add_f32_e32 v179, v43, v59
	v_add_f32_e32 v178, v179, v178
	v_sub_f32_e32 v44, v44, v0
	v_sub_f32_e32 v45, v45, v0
	v_exp_f32_e32 v44, v44
	v_exp_f32_e32 v45, v45
	v_add_f32_e32 v179, v44, v60
	v_add_f32_e32 v178, v179, v178
	v_add_f32_e32 v179, v45, v61
	v_add_f32_e32 v178, v179, v178
	v_sub_f32_e32 v46, v46, v0
	v_sub_f32_e32 v47, v47, v0
	v_exp_f32_e32 v46, v46
	v_exp_f32_e32 v47, v47
	v_add_f32_e32 v179, v46, v62
	v_add_f32_e32 v178, v179, v178
	v_add_f32_e32 v179, v47, v63
	v_add_f32_e32 v178, v179, v178
	v_sub_f32_e32 v48, v48, v0
	v_sub_f32_e32 v49, v49, v0
	v_exp_f32_e32 v48, v48
	v_exp_f32_e32 v49, v49
	v_add_f32_e32 v179, v48, v64
	v_add_f32_e32 v178, v179, v178
	v_add_f32_e32 v179, v49, v65
	v_add_f32_e32 v178, v179, v178
	v_cvt_pk_bf16_f32 v232, v42, v43
	v_cvt_pk_bf16_f32 v233, v44, v45
	v_cvt_pk_bf16_f32 v234, v46, v47
	v_cvt_pk_bf16_f32 v235, v48, v49
	s_waitcnt lgkmcnt(0)
	s_nop 0
	v_mfma_f32_32x32x16_bf16 v[18:33], v[224:227], v[232:235], v[18:33]
	v_mfma_f32_32x32x16_bf16 v[2:17], v[228:231], v[232:235], v[2:17]
	v_add_f32_e32 v121, v178, v121
	v_mov_b32_e32 v122, v0

; #define LAS __attribute__((address_space(3)))
; __device__ __forceinline__ unsigned pk2(float lo, float hi) { f32x2 v = {lo, hi}; bf16x2_t b = __builtin_convertvector(v, bf16x2_t); return __builtin_bit_cast(unsigned, b); }
; template <bool MLA>
; __device__ __forceinline__ void attn_unit(LAS unsigned char* lds, const bf16_t* Q, const bf16_t* Kp, const bf16_t* V, bf16_t* O, const float* ssq_qn, const float* ssq_qr, const float* cl, int b, int h, int qb) {
;     ...
;             float ls = 0.f;
; #pragma unroll
;             for (int i = 0; i < 16; ++i) { p0[i] = __builtin_amdgcn_exp2f(p0[i] - m_new); p1[i] = __builtin_amdgcn_exp2f(p1[i] - m_new); ls += p0[i] + p1[i]; }
;             if (__any(m_new > m_run)) {
;                 const float alpha = __builtin_amdgcn_exp2f(m_run - m_new);
;                 l_run *= alpha;
; #pragma unroll
;                 for (int i = 0; i < 16; ++i) { o0[i] *= alpha; o1[i] *= alpha; }
;             }
;             l_run += ls; m_run = m_new;
;             bf16x8 pb[4];
; #pragma unroll
;             for (int s = 0; s < 4; ++s) { u32x4 wv;
; #pragma unroll
;                 for (int jj = 0; jj < 4; ++jj) wv[jj] = (s < 2) ? pk2(p0[8 * (s & 1) + 2 * jj], p0[8 * (s & 1) + 2 * jj + 1]) : pk2(p1[8 * (s & 1) + 2 * jj], p1[8 * (s & 1) + 2 * jj + 1]);
;                 pb[s] = __builtin_bit_cast(bf16x8, wv); }
;             const LAS unsigned char* vb = lds + VOFF + buf * VBUF + (4 * hh + ((r & 15) >> 2)) * VP + (16 * (r >> 4) + 4 * (r & 3)) * 2;
; #pragma unroll
;             for (int s = 0; s < 4; ++s) {
;                 const v4i16_t lo0 = __builtin_amdgcn_ds_read_tr16_b64_v4i16((LAS v4i16_t*)(vb + s * 16 * VP)), hi0 = __builtin_amdgcn_ds_read_tr16_b64_v4i16((LAS v4i16_t*)(vb + s * 16 * VP + 8 * VP));
;                 const v4i16_t lo1 = __builtin_amdgcn_ds_read_tr16_b64_v4i16((LAS v4i16_t*)(vb + s * 16 * VP + 64)), hi1 = __builtin_amdgcn_ds_read_tr16_b64_v4i16((LAS v4i16_t*)(vb + s * 16 * VP + 8 * VP + 64));
;                 const bf16x8 a0 = (bf16x8){lo0[0], lo0[1], lo0[2], lo0[3], hi0[0], hi0[1], hi0[2], hi0[3]}, a1 = (bf16x8){lo1[0], lo1[1], lo1[2], lo1[3], hi1[0], hi1[1], hi1[2], hi1[3]};
;                 o0 = __builtin_amdgcn_mfma_f32_32x32x16_bf16(a0, pb[s], o0, 0, 0, 0);
;                 o1 = __builtin_amdgcn_mfma_f32_32x32x16_bf16(a1, pb[s], o1, 0, 0, 0);
;             }
.LBB0_384:
	s_mul_i32 s8, s42, 0x3000
	v_add_u32_e32 v130, s8, v109
	ds_read_b64_tr_b16 v[200:201], v130 offset:26624
	ds_read_b64_tr_b16 v[202:203], v130 offset:28160
	ds_read_b64_tr_b16 v[204:205], v130 offset:26688
	ds_read_b64_tr_b16 v[206:207], v130 offset:28224
	ds_read_b64_tr_b16 v[208:209], v130 offset:29696
	ds_read_b64_tr_b16 v[210:211], v130 offset:31232
	ds_read_b64_tr_b16 v[212:213], v130 offset:29760
	ds_read_b64_tr_b16 v[214:215], v130 offset:31296
	ds_read_b64_tr_b16 v[216:217], v130 offset:32768
	ds_read_b64_tr_b16 v[218:219], v130 offset:34304
	ds_read_b64_tr_b16 v[220:221], v130 offset:32832
	ds_read_b64_tr_b16 v[222:223], v130 offset:34368
	v_sub_f32_e32 v50, v50, v0
	v_sub_f32_e32 v51, v51, v0
	v_exp_f32_e32 v50, v50
	v_exp_f32_e32 v51, v51
	v_sub_f32_e32 v52, v52, v0
	v_sub_f32_e32 v53, v53, v0
	v_exp_f32_e32 v52, v52
	v_exp_f32_e32 v53, v53
	v_sub_f32_e32 v54, v54, v0
	v_sub_f32_e32 v55, v55, v0
	v_exp_f32_e32 v54, v54
	v_exp_f32_e32 v55, v55
	v_sub_f32_e32 v56, v56, v0
	v_sub_f32_e32 v57, v57, v0
	v_exp_f32_e32 v56, v56
	v_exp_f32_e32 v57, v57
	v_cvt_pk_bf16_f32 v180, v50, v51
	v_cvt_pk_bf16_f32 v181, v52, v53
	v_cvt_pk_bf16_f32 v182, v54, v55
	v_cvt_pk_bf16_f32 v183, v56, v57
	s_waitcnt lgkmcnt(8)
	ds_read_b64_tr_b16 v[224:225], v130 offset:35840
	ds_read_b64_tr_b16 v[226:227], v130 offset:37376
	ds_read_b64_tr_b16 v[228:229], v130 offset:35904
	ds_read_b64_tr_b16 v[230:231], v130 offset:37440
	v_mfma_f32_32x32x16_bf16 v[18:33], v[200:203], v[180:183], v[18:33]
	v_mfma_f32_32x32x16_bf16 v[2:17], v[204:207], v[180:183], v[2:17]
	v_sub_f32_e32 v58, v58, v0
	v_sub_f32_e32 v59, v59, v0
	v_exp_f32_e32 v58, v58
	v_exp_f32_e32 v59, v59
	v_sub_f32_e32 v60, v60, v0
	v_sub_f32_e32 v61, v61, v0
	v_exp_f32_e32 v60, v60
	v_exp_f32_e32 v61, v61
	v_sub_f32_e32 v62, v62, v0
	v_sub_f32_e32 v63, v63, v0
	v_exp_f32_e32 v62, v62
	v_exp_f32_e32 v63, v63
	v_sub_f32_e32 v64, v64, v0
	v_sub_f32_e32 v65, v65, v0
	v_exp_f32_e32 v64, v64
	v_exp_f32_e32 v65, v65
	v_cvt_pk_bf16_f32 v184, v58, v59
	v_cvt_pk_bf16_f32 v185, v60, v61
	v_cvt_pk_bf16_f32 v186, v62, v63
	v_cvt_pk_bf16_f32 v187, v64, v65
	s_waitcnt lgkmcnt(8)
	s_nop 0
	v_mfma_f32_32x32x16_bf16 v[18:33], v[208:211], v[184:187], v[18:33]
	v_mfma_f32_32x32x16_bf16 v[2:17], v[212:215], v[184:187], v[2:17]
	v_sub_f32_e32 v34, v34, v0
	v_sub_f32_e32 v35, v35, v0
	v_exp_f32_e32 v34, v34
	v_exp_f32_e32 v35, v35
	v_add_f32_e32 v179, v34, v50
	v_add_f32_e32 v178, 0, v179
	v_add_f32_e32 v179, v35, v51
	v_add_f32_e32 v178, v179, v178
	v_sub_f32_e32 v36, v36, v0
	v_sub_f32_e32 v37, v37, v0
	v_exp_f32_e32 v36, v36
	v_exp_f32_e32 v37, v37
	v_add_f32_e32 v179, v36, v52
	v_add_f32_e32 v178, v179, v178
	v_add_f32_e32 v179, v37, v53
	v_add_f32_e32 v178, v179, v178
	v_sub_f32_e32 v38, v38, v0
	v_sub_f32_e32 v39, v39, v0
	v_exp_f32_e32 v38, v38
	v_exp_f32_e32 v39, v39
	v_add_f32_e32 v179, v38, v54
	v_add_f32_e32 v178, v179, v178
	v_add_f32_e32 v179, v39, v55
	v_add_f32_e32 v178, v179, v178
	v_sub_f32_e32 v40, v40, v0
	v_sub_f32_e32 v41, v41, v0
	v_exp_f32_e32 v40, v40
	v_exp_f32_e32 v41, v41
	v_add_f32_e32 v179, v40, v56
	v_add_f32_e32 v178, v179, v178
	v_add_f32_e32 v179, v41, v57
	v_add_f32_e32 v178, v179, v178
	v_cvt_pk_bf16_f32 v188, v34, v35
	v_cvt_pk_bf16_f32 v189, v36, v37
	v_cvt_pk_bf16_f32 v190, v38, v39
	v_cvt_pk_bf16_f32 v191, v40, v41
	s_waitcnt lgkmcnt(4)
	s_nop 0
	v_mfma_f32_32x32x16_bf16 v[18:33], v[216:219], v[188:191], v[18:33]
	v_mfma_f32_32x32x16_bf16 v[2:17], v[220:223], v[188:191], v[2:17]
	v_sub_f32_e32 v42, v42, v0
	v_sub_f32_e32 v43, v43, v0
	v_exp_f32_e32 v42, v42
	v_exp_f32_e32 v43, v43
	v_add_f32_e32 v179, v42, v58
	v_add_f32_e32 v178, v179, v178
	v_add_f32_e32 v179, v43, v59
	v_add_f32_e32 v178, v179, v178
	v_sub_f32_e32 v44, v44, v0
	v_sub_f32_e32 v45, v45, v0
	v_exp_f32_e32 v44, v44
	v_exp_f32_e32 v45, v45
	v_add_f32_e32 v179, v44, v60
	v_add_f32_e32 v178, v179, v178
	v_add_f32_e32 v179, v45, v61
	v_add_f32_e32 v178, v179, v178
	v_sub_f32_e32 v46, v46, v0
	v_sub_f32_e32 v47, v47, v0
	v_exp_f32_e32 v46, v46
	v_exp_f32_e32 v47, v47
	v_add_f32_e32 v179, v46, v62
	v_add_f32_e32 v178, v179, v178
	v_add_f32_e32 v179, v47, v63
	v_add_f32_e32 v178, v179, v178
	v_sub_f32_e32 v48, v48, v0
	v_sub_f32_e32 v49, v49, v0
	v_exp_f32_e32 v48, v48
	v_exp_f32_e32 v49, v49
	v_add_f32_e32 v179, v48, v64
	v_add_f32_e32 v178, v179, v178
	v_add_f32_e32 v179, v49, v65
	v_add_f32_e32 v178, v179, v178
	v_cvt_pk_bf16_f32 v232, v42, v43
	v_cvt_pk_bf16_f32 v233, v44, v45
	v_cvt_pk_bf16_f32 v234, v46, v47
	v_cvt_pk_bf16_f32 v235, v48, v49
	s_waitcnt lgkmcnt(0)
	s_nop 0
	v_mfma_f32_32x32x16_bf16 v[18:33], v[224:227], v[232:235], v[18:33]
	v_mfma_f32_32x32x16_bf16 v[2:17], v[228:231], v[232:235], v[2:17]
	v_add_f32_e32 v108, v178, v108
	v_mov_b32_e32 v111, v0

; #define LAS __attribute__((address_space(3)))
; __device__ __forceinline__ unsigned pk2(float lo, float hi) { f32x2 v = {lo, hi}; bf16x2_t b = __builtin_convertvector(v, bf16x2_t); return __builtin_bit_cast(unsigned, b); }
; template <bool MLA>
; __device__ __forceinline__ void attn_unit(LAS unsigned char* lds, const bf16_t* Q, const bf16_t* Kp, const bf16_t* V, bf16_t* O, const float* ssq_qn, const float* ssq_qr, const float* cl, int b, int h, int qb) {
;     ...
;             float ls = 0.f;
; #pragma unroll
;             for (int i = 0; i < 16; ++i) { p0[i] = __builtin_amdgcn_exp2f(p0[i] - m_new); p1[i] = __builtin_amdgcn_exp2f(p1[i] - m_new); ls += p0[i] + p1[i]; }
;             if (__any(m_new > m_run)) {
;                 const float alpha = __builtin_amdgcn_exp2f(m_run - m_new);
;                 l_run *= alpha;
; #pragma unroll
;                 for (int i = 0; i < 16; ++i) { o0[i] *= alpha; o1[i] *= alpha; }
;             }
;             l_run += ls; m_run = m_new;
;             bf16x8 pb[4];
; #pragma unroll
;             for (int s = 0; s < 4; ++s) { u32x4 wv;
; #pragma unroll
;                 for (int jj = 0; jj < 4; ++jj) wv[jj] = (s < 2) ? pk2(p0[8 * (s & 1) + 2 * jj], p0[8 * (s & 1) + 2 * jj + 1]) : pk2(p1[8 * (s & 1) + 2 * jj], p1[8 * (s & 1) + 2 * jj + 1]);
;                 pb[s] = __builtin_bit_cast(bf16x8, wv); }
;             const LAS unsigned char* vb = lds + VOFF + buf * VBUF + (4 * hh + ((r & 15) >> 2)) * VP + (16 * (r >> 4) + 4 * (r & 3)) * 2;
; #pragma unroll
;             for (int s = 0; s < 4; ++s) {
;                 const v4i16_t lo0 = __builtin_amdgcn_ds_read_tr16_b64_v4i16((LAS v4i16_t*)(vb + s * 16 * VP)), hi0 = __builtin_amdgcn_ds_read_tr16_b64_v4i16((LAS v4i16_t*)(vb + s * 16 * VP + 8 * VP));
;                 const v4i16_t lo1 = __builtin_amdgcn_ds_read_tr16_b64_v4i16((LAS v4i16_t*)(vb + s * 16 * VP + 64)), hi1 = __builtin_amdgcn_ds_read_tr16_b64_v4i16((LAS v4i16_t*)(vb + s * 16 * VP + 8 * VP + 64));
;                 const bf16x8 a0 = (bf16x8){lo0[0], lo0[1], lo0[2], lo0[3], hi0[0], hi0[1], hi0[2], hi0[3]}, a1 = (bf16x8){lo1[0], lo1[1], lo1[2], lo1[3], hi1[0], hi1[1], hi1[2], hi1[3]};
;                 o0 = __builtin_amdgcn_mfma_f32_32x32x16_bf16(a0, pb[s], o0, 0, 0, 0);
;                 o1 = __builtin_amdgcn_mfma_f32_32x32x16_bf16(a1, pb[s], o1, 0, 0, 0);
;             }
.LBB0_406:
	s_mul_i32 s8, s36, 0x3000
	v_add_u32_e32 v130, s8, v121
	ds_read_b64_tr_b16 v[200:201], v130 offset:26624
	ds_read_b64_tr_b16 v[202:203], v130 offset:28160
	ds_read_b64_tr_b16 v[204:205], v130 offset:26688
	ds_read_b64_tr_b16 v[206:207], v130 offset:28224
	ds_read_b64_tr_b16 v[208:209], v130 offset:29696
	ds_read_b64_tr_b16 v[210:211], v130 offset:31232
	ds_read_b64_tr_b16 v[212:213], v130 offset:29760
	ds_read_b64_tr_b16 v[214:215], v130 offset:31296
	ds_read_b64_tr_b16 v[216:217], v130 offset:32768
	ds_read_b64_tr_b16 v[218:219], v130 offset:34304
	ds_read_b64_tr_b16 v[220:221], v130 offset:32832
	ds_read_b64_tr_b16 v[222:223], v130 offset:34368
	v_sub_f32_e32 v50, v50, v0
	v_sub_f32_e32 v51, v51, v0
	v_exp_f32_e32 v50, v50
	v_exp_f32_e32 v51, v51
	v_sub_f32_e32 v52, v52, v0
	v_sub_f32_e32 v53, v53, v0
	v_exp_f32_e32 v52, v52
	v_exp_f32_e32 v53, v53
	v_sub_f32_e32 v54, v54, v0
	v_sub_f32_e32 v55, v55, v0
	v_exp_f32_e32 v54, v54
	v_exp_f32_e32 v55, v55
	v_sub_f32_e32 v56, v56, v0
	v_sub_f32_e32 v57, v57, v0
	v_exp_f32_e32 v56, v56
	v_exp_f32_e32 v57, v57
	v_cvt_pk_bf16_f32 v180, v50, v51
	v_cvt_pk_bf16_f32 v181, v52, v53
	v_cvt_pk_bf16_f32 v182, v54, v55
	v_cvt_pk_bf16_f32 v183, v56, v57
	s_waitcnt lgkmcnt(8)
	ds_read_b64_tr_b16 v[224:225], v130 offset:35840
	ds_read_b64_tr_b16 v[226:227], v130 offset:37376
	ds_read_b64_tr_b16 v[228:229], v130 offset:35904
	ds_read_b64_tr_b16 v[230:231], v130 offset:37440
	v_mfma_f32_32x32x16_bf16 v[18:33], v[200:203], v[180:183], v[18:33]
	v_mfma_f32_32x32x16_bf16 v[2:17], v[204:207], v[180:183], v[2:17]
	v_sub_f32_e32 v58, v58, v0
	v_sub_f32_e32 v59, v59, v0
	v_exp_f32_e32 v58, v58
	v_exp_f32_e32 v59, v59
	v_sub_f32_e32 v60, v60, v0
	v_sub_f32_e32 v61, v61, v0
	v_exp_f32_e32 v60, v60
	v_exp_f32_e32 v61, v61
	v_sub_f32_e32 v62, v62, v0
	v_sub_f32_e32 v63, v63, v0
	v_exp_f32_e32 v62, v62
	v_exp_f32_e32 v63, v63
	v_sub_f32_e32 v64, v64, v0
	v_sub_f32_e32 v65, v65, v0
	v_exp_f32_e32 v64, v64
	v_exp_f32_e32 v65, v65
	v_cvt_pk_bf16_f32 v184, v58, v59
	v_cvt_pk_bf16_f32 v185, v60, v61
	v_cvt_pk_bf16_f32 v186, v62, v63
	v_cvt_pk_bf16_f32 v187, v64, v65
	s_waitcnt lgkmcnt(8)
	s_nop 0
	v_mfma_f32_32x32x16_bf16 v[18:33], v[208:211], v[184:187], v[18:33]
	v_mfma_f32_32x32x16_bf16 v[2:17], v[212:215], v[184:187], v[2:17]
	v_sub_f32_e32 v34, v34, v0
	v_sub_f32_e32 v35, v35, v0
	v_exp_f32_e32 v34, v34
	v_exp_f32_e32 v35, v35
	v_add_f32_e32 v179, v34, v50
	v_add_f32_e32 v178, 0, v179
	v_add_f32_e32 v179, v35, v51
	v_add_f32_e32 v178, v179, v178
	v_sub_f32_e32 v36, v36, v0
	v_sub_f32_e32 v37, v37, v0
	v_exp_f32_e32 v36, v36
	v_exp_f32_e32 v37, v37
	v_add_f32_e32 v179, v36, v52
	v_add_f32_e32 v178, v179, v178
	v_add_f32_e32 v179, v37, v53
	v_add_f32_e32 v178, v179, v178
	v_sub_f32_e32 v38, v38, v0
	v_sub_f32_e32 v39, v39, v0
	v_exp_f32_e32 v38, v38
	v_exp_f32_e32 v39, v39
	v_add_f32_e32 v179, v38, v54
	v_add_f32_e32 v178, v179, v178
	v_add_f32_e32 v179, v39, v55
	v_add_f32_e32 v178, v179, v178
	v_sub_f32_e32 v40, v40, v0
	v_sub_f32_e32 v41, v41, v0
	v_exp_f32_e32 v40, v40
	v_exp_f32_e32 v41, v41
	v_add_f32_e32 v179, v40, v56
	v_add_f32_e32 v178, v179, v178
	v_add_f32_e32 v179, v41, v57
	v_add_f32_e32 v178, v179, v178
	v_cvt_pk_bf16_f32 v188, v34, v35
	v_cvt_pk_bf16_f32 v189, v36, v37
	v_cvt_pk_bf16_f32 v190, v38, v39
	v_cvt_pk_bf16_f32 v191, v40, v41
	s_waitcnt lgkmcnt(4)
	s_nop 0
	v_mfma_f32_32x32x16_bf16 v[18:33], v[216:219], v[188:191], v[18:33]
	v_mfma_f32_32x32x16_bf16 v[2:17], v[220:223], v[188:191], v[2:17]
	v_sub_f32_e32 v42, v42, v0
	v_sub_f32_e32 v43, v43, v0
	v_exp_f32_e32 v42, v42
	v_exp_f32_e32 v43, v43
	v_add_f32_e32 v179, v42, v58
	v_add_f32_e32 v178, v179, v178
	v_add_f32_e32 v179, v43, v59
	v_add_f32_e32 v178, v179, v178
	v_sub_f32_e32 v44, v44, v0
	v_sub_f32_e32 v45, v45, v0
	v_exp_f32_e32 v44, v44
	v_exp_f32_e32 v45, v45
	v_add_f32_e32 v179, v44, v60
	v_add_f32_e32 v178, v179, v178
	v_add_f32_e32 v179, v45, v61
	v_add_f32_e32 v178, v179, v178
	v_sub_f32_e32 v46, v46, v0
	v_sub_f32_e32 v47, v47, v0
	v_exp_f32_e32 v46, v46
	v_exp_f32_e32 v47, v47
	v_add_f32_e32 v179, v46, v62
	v_add_f32_e32 v178, v179, v178
	v_add_f32_e32 v179, v47, v63
	v_add_f32_e32 v178, v179, v178
	v_sub_f32_e32 v48, v48, v0
	v_sub_f32_e32 v49, v49, v0
	v_exp_f32_e32 v48, v48
	v_exp_f32_e32 v49, v49
	v_add_f32_e32 v179, v48, v64
	v_add_f32_e32 v178, v179, v178
	v_add_f32_e32 v179, v49, v65
	v_add_f32_e32 v178, v179, v178
	v_cvt_pk_bf16_f32 v232, v42, v43
	v_cvt_pk_bf16_f32 v233, v44, v45
	v_cvt_pk_bf16_f32 v234, v46, v47
	v_cvt_pk_bf16_f32 v235, v48, v49
	s_waitcnt lgkmcnt(0)
	s_nop 0
	v_mfma_f32_32x32x16_bf16 v[18:33], v[224:227], v[232:235], v[18:33]
	v_mfma_f32_32x32x16_bf16 v[2:17], v[228:231], v[232:235], v[2:17]
	v_add_f32_e32 v122, v178, v122
	v_mov_b32_e32 v123, v0

; #define LAS __attribute__((address_space(3)))
; __device__ __forceinline__ unsigned pk2(float lo, float hi) { f32x2 v = {lo, hi}; bf16x2_t b = __builtin_convertvector(v, bf16x2_t); return __builtin_bit_cast(unsigned, b); }
; template <bool MLA>
; __device__ __forceinline__ void attn_unit(LAS unsigned char* lds, const bf16_t* Q, const bf16_t* Kp, const bf16_t* V, bf16_t* O, const float* ssq_qn, const float* ssq_qr, const float* cl, int b, int h, int qb) {
;     ...
;             float ls = 0.f;
; #pragma unroll
;             for (int i = 0; i < 16; ++i) { p0[i] = __builtin_amdgcn_exp2f(p0[i] - m_new); p1[i] = __builtin_amdgcn_exp2f(p1[i] - m_new); ls += p0[i] + p1[i]; }
;             if (__any(m_new > m_run)) {
;                 const float alpha = __builtin_amdgcn_exp2f(m_run - m_new);
;                 l_run *= alpha;
; #pragma unroll
;                 for (int i = 0; i < 16; ++i) { o0[i] *= alpha; o1[i] *= alpha; }
;             }
;             l_run += ls; m_run = m_new;
;             bf16x8 pb[4];
; #pragma unroll
;             for (int s = 0; s < 4; ++s) { u32x4 wv;
; #pragma unroll
;                 for (int jj = 0; jj < 4; ++jj) wv[jj] = (s < 2) ? pk2(p0[8 * (s & 1) + 2 * jj], p0[8 * (s & 1) + 2 * jj + 1]) : pk2(p1[8 * (s & 1) + 2 * jj], p1[8 * (s & 1) + 2 * jj + 1]);
;                 pb[s] = __builtin_bit_cast(bf16x8, wv); }
;             const LAS unsigned char* vb = lds + VOFF + buf * VBUF + (4 * hh + ((r & 15) >> 2)) * VP + (16 * (r >> 4) + 4 * (r & 3)) * 2;
; #pragma unroll
;             for (int s = 0; s < 4; ++s) {
;                 const v4i16_t lo0 = __builtin_amdgcn_ds_read_tr16_b64_v4i16((LAS v4i16_t*)(vb + s * 16 * VP)), hi0 = __builtin_amdgcn_ds_read_tr16_b64_v4i16((LAS v4i16_t*)(vb + s * 16 * VP + 8 * VP));
;                 const v4i16_t lo1 = __builtin_amdgcn_ds_read_tr16_b64_v4i16((LAS v4i16_t*)(vb + s * 16 * VP + 64)), hi1 = __builtin_amdgcn_ds_read_tr16_b64_v4i16((LAS v4i16_t*)(vb + s * 16 * VP + 8 * VP + 64));
;                 const bf16x8 a0 = (bf16x8){lo0[0], lo0[1], lo0[2], lo0[3], hi0[0], hi0[1], hi0[2], hi0[3]}, a1 = (bf16x8){lo1[0], lo1[1], lo1[2], lo1[3], hi1[0], hi1[1], hi1[2], hi1[3]};
;                 o0 = __builtin_amdgcn_mfma_f32_32x32x16_bf16(a0, pb[s], o0, 0, 0, 0);
;                 o1 = __builtin_amdgcn_mfma_f32_32x32x16_bf16(a1, pb[s], o1, 0, 0, 0);
;             }
.LBB0_428:
	s_mul_i32 s8, s16, 0x3000
	v_add_u32_e32 v130, s8, v109
	ds_read_b64_tr_b16 v[200:201], v130 offset:26624
	ds_read_b64_tr_b16 v[202:203], v130 offset:28160
	ds_read_b64_tr_b16 v[204:205], v130 offset:26688
	ds_read_b64_tr_b16 v[206:207], v130 offset:28224
	ds_read_b64_tr_b16 v[208:209], v130 offset:29696
	ds_read_b64_tr_b16 v[210:211], v130 offset:31232
	ds_read_b64_tr_b16 v[212:213], v130 offset:29760
	ds_read_b64_tr_b16 v[214:215], v130 offset:31296
	ds_read_b64_tr_b16 v[216:217], v130 offset:32768
	ds_read_b64_tr_b16 v[218:219], v130 offset:34304
	ds_read_b64_tr_b16 v[220:221], v130 offset:32832
	ds_read_b64_tr_b16 v[222:223], v130 offset:34368
	v_sub_f32_e32 v50, v50, v0
	v_sub_f32_e32 v51, v51, v0
	v_exp_f32_e32 v50, v50
	v_exp_f32_e32 v51, v51
	v_sub_f32_e32 v52, v52, v0
	v_sub_f32_e32 v53, v53, v0
	v_exp_f32_e32 v52, v52
	v_exp_f32_e32 v53, v53
	v_sub_f32_e32 v54, v54, v0
	v_sub_f32_e32 v55, v55, v0
	v_exp_f32_e32 v54, v54
	v_exp_f32_e32 v55, v55
	v_sub_f32_e32 v56, v56, v0
	v_sub_f32_e32 v57, v57, v0
	v_exp_f32_e32 v56, v56
	v_exp_f32_e32 v57, v57
	v_cvt_pk_bf16_f32 v180, v50, v51
	v_cvt_pk_bf16_f32 v181, v52, v53
	v_cvt_pk_bf16_f32 v182, v54, v55
	v_cvt_pk_bf16_f32 v183, v56, v57
	s_waitcnt lgkmcnt(8)
	ds_read_b64_tr_b16 v[224:225], v130 offset:35840
	ds_read_b64_tr_b16 v[226:227], v130 offset:37376
	ds_read_b64_tr_b16 v[228:229], v130 offset:35904
	ds_read_b64_tr_b16 v[230:231], v130 offset:37440
	v_mfma_f32_32x32x16_bf16 v[18:33], v[200:203], v[180:183], v[18:33]
	v_mfma_f32_32x32x16_bf16 v[2:17], v[204:207], v[180:183], v[2:17]
	v_sub_f32_e32 v58, v58, v0
	v_sub_f32_e32 v59, v59, v0
	v_exp_f32_e32 v58, v58
	v_exp_f32_e32 v59, v59
	v_sub_f32_e32 v60, v60, v0
	v_sub_f32_e32 v61, v61, v0
	v_exp_f32_e32 v60, v60
	v_exp_f32_e32 v61, v61
	v_sub_f32_e32 v62, v62, v0
	v_sub_f32_e32 v63, v63, v0
	v_exp_f32_e32 v62, v62
	v_exp_f32_e32 v63, v63
	v_sub_f32_e32 v64, v64, v0
	v_sub_f32_e32 v65, v65, v0
	v_exp_f32_e32 v64, v64
	v_exp_f32_e32 v65, v65
	v_cvt_pk_bf16_f32 v184, v58, v59
	v_cvt_pk_bf16_f32 v185, v60, v61
	v_cvt_pk_bf16_f32 v186, v62, v63
	v_cvt_pk_bf16_f32 v187, v64, v65
	s_waitcnt lgkmcnt(8)
	s_nop 0
	v_mfma_f32_32x32x16_bf16 v[18:33], v[208:211], v[184:187], v[18:33]
	v_mfma_f32_32x32x16_bf16 v[2:17], v[212:215], v[184:187], v[2:17]
	v_sub_f32_e32 v34, v34, v0
	v_sub_f32_e32 v35, v35, v0
	v_exp_f32_e32 v34, v34
	v_exp_f32_e32 v35, v35
	v_add_f32_e32 v179, v34, v50
	v_add_f32_e32 v178, 0, v179
	v_add_f32_e32 v179, v35, v51
	v_add_f32_e32 v178, v179, v178
	v_sub_f32_e32 v36, v36, v0
	v_sub_f32_e32 v37, v37, v0
	v_exp_f32_e32 v36, v36
	v_exp_f32_e32 v37, v37
	v_add_f32_e32 v179, v36, v52
	v_add_f32_e32 v178, v179, v178
	v_add_f32_e32 v179, v37, v53
	v_add_f32_e32 v178, v179, v178
	v_sub_f32_e32 v38, v38, v0
	v_sub_f32_e32 v39, v39, v0
	v_exp_f32_e32 v38, v38
	v_exp_f32_e32 v39, v39
	v_add_f32_e32 v179, v38, v54
	v_add_f32_e32 v178, v179, v178
	v_add_f32_e32 v179, v39, v55
	v_add_f32_e32 v178, v179, v178
	v_sub_f32_e32 v40, v40, v0
	v_sub_f32_e32 v41, v41, v0
	v_exp_f32_e32 v40, v40
	v_exp_f32_e32 v41, v41
	v_add_f32_e32 v179, v40, v56
	v_add_f32_e32 v178, v179, v178
	v_add_f32_e32 v179, v41, v57
	v_add_f32_e32 v178, v179, v178
	v_cvt_pk_bf16_f32 v188, v34, v35
	v_cvt_pk_bf16_f32 v189, v36, v37
	v_cvt_pk_bf16_f32 v190, v38, v39
	v_cvt_pk_bf16_f32 v191, v40, v41
	s_waitcnt lgkmcnt(4)
	s_nop 0
	v_mfma_f32_32x32x16_bf16 v[18:33], v[216:219], v[188:191], v[18:33]
	v_mfma_f32_32x32x16_bf16 v[2:17], v[220:223], v[188:191], v[2:17]
	v_sub_f32_e32 v42, v42, v0
	v_sub_f32_e32 v43, v43, v0
	v_exp_f32_e32 v42, v42
	v_exp_f32_e32 v43, v43
	v_add_f32_e32 v179, v42, v58
	v_add_f32_e32 v178, v179, v178
	v_add_f32_e32 v179, v43, v59
	v_add_f32_e32 v178, v179, v178
	v_sub_f32_e32 v44, v44, v0
	v_sub_f32_e32 v45, v45, v0
	v_exp_f32_e32 v44, v44
	v_exp_f32_e32 v45, v45
	v_add_f32_e32 v179, v44, v60
	v_add_f32_e32 v178, v179, v178
	v_add_f32_e32 v179, v45, v61
	v_add_f32_e32 v178, v179, v178
	v_sub_f32_e32 v46, v46, v0
	v_sub_f32_e32 v47, v47, v0
	v_exp_f32_e32 v46, v46
	v_exp_f32_e32 v47, v47
	v_add_f32_e32 v179, v46, v62
	v_add_f32_e32 v178, v179, v178
	v_add_f32_e32 v179, v47, v63
	v_add_f32_e32 v178, v179, v178
	v_sub_f32_e32 v48, v48, v0
	v_sub_f32_e32 v49, v49, v0
	v_exp_f32_e32 v48, v48
	v_exp_f32_e32 v49, v49
	v_add_f32_e32 v179, v48, v64
	v_add_f32_e32 v178, v179, v178
	v_add_f32_e32 v179, v49, v65
	v_add_f32_e32 v178, v179, v178
	v_cvt_pk_bf16_f32 v232, v42, v43
	v_cvt_pk_bf16_f32 v233, v44, v45
	v_cvt_pk_bf16_f32 v234, v46, v47
	v_cvt_pk_bf16_f32 v235, v48, v49
	s_waitcnt lgkmcnt(0)
	s_nop 0
	v_mfma_f32_32x32x16_bf16 v[18:33], v[224:227], v[232:235], v[18:33]
	v_mfma_f32_32x32x16_bf16 v[2:17], v[228:231], v[232:235], v[2:17]
	v_add_f32_e32 v108, v178, v108
	v_mov_b32_e32 v111, v0
